# GLA chunk-summary units: the two 64-lane inclusive scans per d (7 of 8 blocks) on DPP row_shr/row_bcast plus v_readlane totals instead of 14 dependent ds_bpermute round trips
# speedup vs baseline: 1.0014x; 1.0014x over previous
; #define LAS __attribute__((address_space(3)))
; __device__ __forceinline__ float bflo(unsigned w) { return __uint_as_float(w << 16); }
; __device__ __forceinline__ float bfhi(unsigned w) { return __uint_as_float(w & 0xffff0000u); }
; __device__ __forceinline__ unsigned short f2bf(float f) { return (unsigned short)(cvt_pk_bf16(f, 0.f) & 0xffffu); }
; __device__ __forceinline__ float logsig(float x) { return fminf(x, 0.f) - __logf(1.f + __expf(-fabsf(x))); }
; __device__ __forceinline__ float wave_incl_scan(float x, int lane) {
; #pragma unroll
;     for (int o = 1; o < 64; o <<= 1) { const float t = __shfl_up(x, o); if (lane >= o) x += t; }
;     return x;
; }
; __device__ __forceinline__ void gla_p1(CArgs& a, int l, int cc, int h, LAS float* L, int dup, bool stagew) {
;     ...
;     for (int dd = 0; dd < 8; ++dd) { const int d = 8 * wid + dd;
;         float pf = L[GL_BF + d], pb = L[GL_BB + d];
; #pragma unroll
;         for (int q = 0; q < 4; ++q) { const f32x4 wf4 = *(const LAS f32x4*)(L + GL_WF + d * 16 + 4 * q), wb4 = *(const LAS f32x4*)(L + GL_WB + d * 16 + 4 * q);
; #pragma unroll
;             for (int e = 0; e < 4; ++e) { pf += cgf[4 * q + e] * wf4[e]; pb += cgb[4 * q + e] * wb4[e]; } }
;         const float gf = logsig(pf) * (1.f / 16.f), gb = logsig(pb) * (1.f / 16.f);
;         const float cf = wave_incl_scan(gf, lane), pbi = wave_incl_scan(gb, lane);
;         const float totf = __shfl(cf, 63), totb = __shfl(pbi, 63);
;         const float cb = totb - pbi + gb;
;         const float k = (dd & 1) ? bfhi(kw[dd >> 1]) : bflo(kw[dd >> 1]), q = ((dd & 1) ? bfhi(qw[dd >> 1]) : bflo(qw[dd >> 1])) * 0.125f;
;         oqf[dd] = q * __expf(cf); oqb[dd] = q * __expf(cb); okf[dd] = k * __expf(-cf); okb[dd] = k * __expf(-cb);
;         *(LAS unsigned short*)(B + GB_QDF + (d * HS + lane) * 2) = f2bf(k * __expf(totf - cf));
;         *(LAS unsigned short*)(B + GB_QDB + (d * HS + lane) * 2) = f2bf(k * __expf(totb - cb));
;         if (lane == 0) { DEC[(size_t)slot * 64 + d] = __expf(totf); DEC[(size_t)(slot + 1) * 64 + d] = __expf(totb); } }
.LBB0_144:
	s_or_b64 exec, exec, s[14:15]
	s_add_i32 s6, s4, 0x24e04
	s_or_b32 s5, s22, 1
	v_mov_b32_e32 v54, s6
	s_add_i32 s6, s4, 0x24f04
	v_mov_b32_e32 v55, s6
	s_lshl_b32 s6, s5, 6
	s_add_i32 s6, s6, 0
	s_add_i32 s7, s6, 0x22e00
	v_mov_b32_e32 v66, s7
	ds_read_b32 v86, v54
	ds_read_b32 v87, v55
	ds_read_b128 v[54:57], v66
	ds_read_b128 v[58:61], v66 offset:16
	ds_read_b128 v[62:65], v66 offset:32
	s_add_i32 s6, s6, 0x23e00
	v_mov_b32_e32 v82, s6
	s_waitcnt lgkmcnt(2)
	v_fmac_f32_e32 v86, v54, v50
	v_fmac_f32_e32 v86, v55, v47
	v_fmac_f32_e32 v86, v56, v45
	v_fmac_f32_e32 v86, v57, v43
	s_waitcnt lgkmcnt(1)
	v_fmac_f32_e32 v86, v58, v41
	v_fmac_f32_e32 v86, v59, v39
	v_fmac_f32_e32 v86, v60, v37
	v_fmac_f32_e32 v86, v61, v35
	ds_read_b128 v[66:69], v66 offset:48
	ds_read_b128 v[70:73], v82
	s_waitcnt lgkmcnt(2)
	v_fmac_f32_e32 v86, v62, v33
	v_fmac_f32_e32 v86, v63, v31
	v_fmac_f32_e32 v86, v64, v29
	v_fmac_f32_e32 v86, v65, v28
	s_waitcnt lgkmcnt(1)
	v_fmac_f32_e32 v86, v66, v27
	s_waitcnt lgkmcnt(0)
	v_fmac_f32_e32 v87, v70, v49
	v_fmac_f32_e32 v86, v67, v26
	ds_read_b128 v[74:77], v82 offset:16
	ds_read_b128 v[78:81], v82 offset:32
	ds_read_b128 v[82:85], v82 offset:48
	v_fmac_f32_e32 v87, v71, v48
	v_fmac_f32_e32 v86, v68, v25
	v_fmac_f32_e32 v87, v72, v46
	v_fmac_f32_e32 v86, v69, v24
	v_fmac_f32_e32 v87, v73, v44
	v_mul_f32_e64 v54, |v86|, s27
	s_waitcnt lgkmcnt(2)
	v_fmac_f32_e32 v87, v74, v42
	v_exp_f32_e32 v54, v54
	v_fmac_f32_e32 v87, v75, v40
	v_fmac_f32_e32 v87, v76, v38
	v_fmac_f32_e32 v87, v77, v36
	s_waitcnt lgkmcnt(1)
	v_fmac_f32_e32 v87, v78, v34
	v_add_f32_e32 v54, 1.0, v54
	v_fmac_f32_e32 v87, v79, v32
	v_cmp_gt_f32_e64 s[52:53], s26, v54
	v_fmac_f32_e32 v87, v80, v30
	v_fmac_f32_e32 v87, v81, v19
	v_cndmask_b32_e64 v55, 0, 32, s[52:53]
	v_ldexp_f32 v54, v54, v55
	s_waitcnt lgkmcnt(0)
	v_fmac_f32_e32 v87, v82, v20
	v_log_f32_e32 v54, v54
	v_fmac_f32_e32 v87, v83, v21
	v_fmac_f32_e32 v87, v84, v17
	v_fmac_f32_e32 v87, v85, v18
	v_mul_f32_e32 v56, 0x3f317217, v54
	v_mul_f32_e64 v57, |v87|, s27
	v_fma_f32 v56, v54, s79, -v56
	v_exp_f32_e32 v57, v57
	v_fmac_f32_e32 v56, 0x3377d1cf, v54
	v_fmac_f32_e32 v56, 0x3f317217, v54
	v_cmp_lt_f32_e64 s[54:55], |v54|, s80
	v_min_f32_e32 v55, 0, v86
	s_mulk_i32 s5, 0x48
	v_cndmask_b32_e64 v54, v54, v56, s[54:55]
	v_cndmask_b32_e64 v56, 0, v225, s[52:53]
	v_sub_f32_e32 v54, v54, v56
	v_add_f32_e32 v56, 1.0, v57
	v_cmp_gt_f32_e64 s[52:53], s26, v56
	v_sub_f32_e32 v54, v55, v54
	v_mul_f32_e32 v55, 0x3d800000, v54
	v_cndmask_b32_e64 v57, 0, 32, s[52:53]
	v_ldexp_f32 v56, v56, v57
	v_log_f32_e32 v56, v56
	v_min_f32_e32 v57, 0, v87
	v_mul_f32_e32 v58, 0x3f317217, v56
	v_fma_f32 v58, v56, s79, -v58
	v_fmac_f32_e32 v58, 0x3377d1cf, v56
	v_fmac_f32_e32 v58, 0x3f317217, v56
	v_cmp_lt_f32_e64 s[54:55], |v56|, s80
	s_nop 1
	v_cndmask_b32_e64 v56, v56, v58, s[54:55]
	v_cndmask_b32_e64 v58, 0, v225, s[52:53]
	v_sub_f32_e32 v56, v56, v58
	v_sub_f32_e32 v56, v57, v56
	v_mul_f32_e32 v57, 0x3d800000, v56
	v_mov_b32_e32 v54, v55
	v_mov_b32_e32 v55, v57
	s_nop 1
	v_add_f32_dpp v54, v54, v54 row_shr:1 row_mask:0xf bank_mask:0xf
	v_add_f32_dpp v55, v55, v55 row_shr:1 row_mask:0xf bank_mask:0xf
	s_nop 0
	v_add_f32_dpp v54, v54, v54 row_shr:2 row_mask:0xf bank_mask:0xf
	v_add_f32_dpp v55, v55, v55 row_shr:2 row_mask:0xf bank_mask:0xf
	s_nop 0
	v_add_f32_dpp v54, v54, v54 row_shr:4 row_mask:0xf bank_mask:0xf
	v_add_f32_dpp v55, v55, v55 row_shr:4 row_mask:0xf bank_mask:0xf
	s_nop 0
	v_add_f32_dpp v54, v54, v54 row_shr:8 row_mask:0xf bank_mask:0xf
	v_add_f32_dpp v55, v55, v55 row_shr:8 row_mask:0xf bank_mask:0xf
	s_nop 0
	v_add_f32_dpp v54, v54, v54 row_bcast:15 row_mask:0xa bank_mask:0xf
	v_add_f32_dpp v55, v55, v55 row_bcast:15 row_mask:0xa bank_mask:0xf
	s_nop 0
	v_add_f32_dpp v54, v54, v54 row_bcast:31 row_mask:0xc bank_mask:0xf
	v_add_f32_dpp v55, v55, v55 row_bcast:31 row_mask:0xc bank_mask:0xf
	s_nop 0
	v_readlane_b32 s98, v54, 63
	v_readlane_b32 s99, v55, 63
	s_nop 1
	v_mov_b32_e32 v58, s98
	v_mov_b32_e32 v57, s99
	s_waitcnt lgkmcnt(1)
	v_sub_f32_e32 v59, v58, v54
	v_mul_f32_e32 v59, 0x3fb8aa3b, v59
	v_exp_f32_e32 v59, v59
	s_waitcnt lgkmcnt(0)
	v_sub_f32_e32 v55, v57, v55
	v_fmac_f32_e32 v55, 0x3d800000, v56
	v_and_b32_e32 v56, 0xffff0000, v6
	v_mul_f32_e32 v6, v59, v56
	v_cvt_pk_bf16_f32 v59, v6, v1
	v_sub_f32_e32 v6, v57, v55
	v_mul_f32_e32 v6, 0x3fb8aa3b, v6
	v_exp_f32_e32 v60, v6
	v_add_u32_e32 v6, s5, v22
	v_lshl_add_u32 v61, v6, 1, 0
	ds_write_b16 v61, v59 offset:33280
	v_mul_f32_e32 v59, v60, v56
	v_cvt_pk_bf16_f32 v59, v59, v1
	ds_write_b16 v61, v59 offset:42496
	s_and_saveexec_b64 s[14:15], s[38:39]
	s_cbranch_execz .LBB0_146
	v_mul_f32_e32 v58, 0x3fb8aa3b, v58
	s_ashr_i32 s23, s22, 31
	v_exp_f32_e32 v58, v58
	s_lshl_b64 s[6:7], s[22:23], 2
	v_mul_f32_e32 v57, 0x3fb8aa3b, v57
	s_add_u32 s30, s18, s6
	v_exp_f32_e32 v57, v57
	s_addc_u32 s31, s21, s7
	s_add_u32 s6, s51, s6
	s_addc_u32 s7, s92, s7
	global_store_dword v1, v58, s[30:31] offset:4
	global_store_dword v1, v57, s[6:7] offset:4
; #define LAS __attribute__((address_space(3)))
; __device__ __forceinline__ float bflo(unsigned w) { return __uint_as_float(w << 16); }
; __device__ __forceinline__ float bfhi(unsigned w) { return __uint_as_float(w & 0xffff0000u); }
; __device__ __forceinline__ unsigned short f2bf(float f) { return (unsigned short)(cvt_pk_bf16(f, 0.f) & 0xffffu); }
; __device__ __forceinline__ float logsig(float x) { return fminf(x, 0.f) - __logf(1.f + __expf(-fabsf(x))); }
; __device__ __forceinline__ float wave_incl_scan(float x, int lane) {
; #pragma unroll
;     for (int o = 1; o < 64; o <<= 1) { const float t = __shfl_up(x, o); if (lane >= o) x += t; }
;     return x;
; }
; __device__ __forceinline__ void gla_p1(CArgs& a, int l, int cc, int h, LAS float* L, int dup, bool stagew) {
;     ...
;     for (int dd = 0; dd < 8; ++dd) { const int d = 8 * wid + dd;
;         float pf = L[GL_BF + d], pb = L[GL_BB + d];
; #pragma unroll
;         for (int q = 0; q < 4; ++q) { const f32x4 wf4 = *(const LAS f32x4*)(L + GL_WF + d * 16 + 4 * q), wb4 = *(const LAS f32x4*)(L + GL_WB + d * 16 + 4 * q);
; #pragma unroll
;             for (int e = 0; e < 4; ++e) { pf += cgf[4 * q + e] * wf4[e]; pb += cgb[4 * q + e] * wb4[e]; } }
;         const float gf = logsig(pf) * (1.f / 16.f), gb = logsig(pb) * (1.f / 16.f);
;         const float cf = wave_incl_scan(gf, lane), pbi = wave_incl_scan(gb, lane);
;         const float totf = __shfl(cf, 63), totb = __shfl(pbi, 63);
;         const float cb = totb - pbi + gb;
;         const float k = (dd & 1) ? bfhi(kw[dd >> 1]) : bflo(kw[dd >> 1]), q = ((dd & 1) ? bfhi(qw[dd >> 1]) : bflo(qw[dd >> 1])) * 0.125f;
;         oqf[dd] = q * __expf(cf); oqb[dd] = q * __expf(cb); okf[dd] = k * __expf(-cf); okb[dd] = k * __expf(-cb);
;         *(LAS unsigned short*)(B + GB_QDF + (d * HS + lane) * 2) = f2bf(k * __expf(totf - cf));
;         *(LAS unsigned short*)(B + GB_QDB + (d * HS + lane) * 2) = f2bf(k * __expf(totb - cb));
;         if (lane == 0) { DEC[(size_t)slot * 64 + d] = __expf(totf); DEC[(size_t)(slot + 1) * 64 + d] = __expf(totb); } }
.LBB0_146:
	s_or_b64 exec, exec, s[14:15]
	s_lshl_b32 s5, s22, 6
	s_add_i32 s6, s4, 0x24e08
	v_mov_b32_e32 v57, s6
	s_add_i32 s6, s4, 0x24f08
	s_add_i32 s5, s5, 0
	v_mov_b32_e32 v58, s6
	s_add_i32 s6, s5, 0x22e80
	v_mov_b32_e32 v70, s6
	ds_read_b32 v57, v57
	ds_read_b32 v90, v58
	ds_read_b128 v[58:61], v70
	ds_read_b128 v[62:65], v70 offset:16
	ds_read_b128 v[66:69], v70 offset:32
	s_add_i32 s7, s5, 0x23e80
	v_mov_b32_e32 v86, s7
	s_waitcnt lgkmcnt(2)
	v_fmac_f32_e32 v57, v58, v50
	v_fmac_f32_e32 v57, v59, v47
	v_fmac_f32_e32 v57, v60, v45
	v_fmac_f32_e32 v57, v61, v43
	s_waitcnt lgkmcnt(1)
	v_fmac_f32_e32 v57, v62, v41
	v_fmac_f32_e32 v57, v63, v39
	v_fmac_f32_e32 v57, v64, v37
	v_fmac_f32_e32 v57, v65, v35
	ds_read_b128 v[70:73], v70 offset:48
	ds_read_b128 v[74:77], v86
	s_waitcnt lgkmcnt(2)
	v_fmac_f32_e32 v57, v66, v33
	v_fmac_f32_e32 v57, v67, v31
	v_fmac_f32_e32 v57, v68, v29
	v_fmac_f32_e32 v57, v69, v28
	s_waitcnt lgkmcnt(1)
	v_fmac_f32_e32 v57, v70, v27
	s_waitcnt lgkmcnt(0)
	v_fmac_f32_e32 v90, v74, v49
	v_fmac_f32_e32 v57, v71, v26
	ds_read_b128 v[78:81], v86 offset:16
	ds_read_b128 v[82:85], v86 offset:32
	ds_read_b128 v[86:89], v86 offset:48
	v_fmac_f32_e32 v90, v75, v48
	v_fmac_f32_e32 v57, v72, v25
	v_fmac_f32_e32 v90, v76, v46
	v_fmac_f32_e32 v57, v73, v24
	v_fmac_f32_e32 v90, v77, v44
	v_mul_f32_e64 v58, |v57|, s27
	s_waitcnt lgkmcnt(2)
	v_fmac_f32_e32 v90, v78, v42
	v_exp_f32_e32 v58, v58
	v_fmac_f32_e32 v90, v79, v40
	v_fmac_f32_e32 v90, v80, v38
	v_fmac_f32_e32 v90, v81, v36
	s_waitcnt lgkmcnt(1)
	v_fmac_f32_e32 v90, v82, v34
	v_add_f32_e32 v58, 1.0, v58
	v_fmac_f32_e32 v90, v83, v32
	v_cmp_gt_f32_e64 s[52:53], s26, v58
	v_fmac_f32_e32 v90, v84, v30
	v_fmac_f32_e32 v90, v85, v19
	v_cndmask_b32_e64 v59, 0, 32, s[52:53]
	v_ldexp_f32 v58, v58, v59
	s_waitcnt lgkmcnt(0)
	v_fmac_f32_e32 v90, v86, v20
	v_log_f32_e32 v58, v58
	v_fmac_f32_e32 v90, v87, v21
	v_fmac_f32_e32 v90, v88, v17
	v_fmac_f32_e32 v90, v89, v18
	v_mul_f32_e32 v59, 0x3f317217, v58
	v_mul_f32_e64 v60, |v90|, s27
	v_fma_f32 v59, v58, s79, -v59
	v_exp_f32_e32 v60, v60
	v_fmac_f32_e32 v59, 0x3377d1cf, v58
	v_fmac_f32_e32 v59, 0x3f317217, v58
	v_cmp_lt_f32_e64 s[54:55], |v58|, s80
	v_min_f32_e32 v57, 0, v57
	v_add_u32_e32 v6, 0x48, v6
	v_cndmask_b32_e64 v58, v58, v59, s[54:55]
	v_cndmask_b32_e64 v59, 0, v225, s[52:53]
	v_sub_f32_e32 v58, v58, v59
	v_add_f32_e32 v59, 1.0, v60
	v_cmp_gt_f32_e64 s[52:53], s26, v59
	v_sub_f32_e32 v57, v57, v58
	v_mul_f32_e32 v58, 0x3d800000, v57
	v_cndmask_b32_e64 v60, 0, 32, s[52:53]
	v_ldexp_f32 v59, v59, v60
	v_log_f32_e32 v59, v59
	v_min_f32_e32 v60, 0, v90
	v_lshl_add_u32 v64, v6, 1, 0
	v_mul_f32_e32 v61, 0x3f317217, v59
	v_fma_f32 v61, v59, s79, -v61
	v_fmac_f32_e32 v61, 0x3377d1cf, v59
	v_fmac_f32_e32 v61, 0x3f317217, v59
	v_cmp_lt_f32_e64 s[54:55], |v59|, s80
	s_nop 1
	v_cndmask_b32_e64 v59, v59, v61, s[54:55]
	v_cndmask_b32_e64 v61, 0, v225, s[52:53]
	v_sub_f32_e32 v59, v59, v61
	v_sub_f32_e32 v59, v60, v59
	v_mul_f32_e32 v60, 0x3d800000, v59
	v_mov_b32_e32 v57, v58
	v_mov_b32_e32 v58, v60
	s_nop 1
	v_add_f32_dpp v57, v57, v57 row_shr:1 row_mask:0xf bank_mask:0xf
	v_add_f32_dpp v58, v58, v58 row_shr:1 row_mask:0xf bank_mask:0xf
	s_nop 0
	v_add_f32_dpp v57, v57, v57 row_shr:2 row_mask:0xf bank_mask:0xf
	v_add_f32_dpp v58, v58, v58 row_shr:2 row_mask:0xf bank_mask:0xf
	s_nop 0
	v_add_f32_dpp v57, v57, v57 row_shr:4 row_mask:0xf bank_mask:0xf
	v_add_f32_dpp v58, v58, v58 row_shr:4 row_mask:0xf bank_mask:0xf
	s_nop 0
	v_add_f32_dpp v57, v57, v57 row_shr:8 row_mask:0xf bank_mask:0xf
	v_add_f32_dpp v58, v58, v58 row_shr:8 row_mask:0xf bank_mask:0xf
	s_nop 0
	v_add_f32_dpp v57, v57, v57 row_bcast:15 row_mask:0xa bank_mask:0xf
	v_add_f32_dpp v58, v58, v58 row_bcast:15 row_mask:0xa bank_mask:0xf
	s_nop 0
	v_add_f32_dpp v57, v57, v57 row_bcast:31 row_mask:0xc bank_mask:0xf
	v_add_f32_dpp v58, v58, v58 row_bcast:31 row_mask:0xc bank_mask:0xf
	s_nop 0
	v_readlane_b32 s98, v57, 63
	v_readlane_b32 s99, v58, 63
	s_nop 1
	v_mov_b32_e32 v61, s98
	v_mov_b32_e32 v60, s99
	s_waitcnt lgkmcnt(1)
	v_sub_f32_e32 v62, v61, v57
	s_waitcnt lgkmcnt(0)
	v_sub_f32_e32 v58, v60, v58
	v_mul_f32_e32 v62, 0x3fb8aa3b, v62
	v_fmac_f32_e32 v58, 0x3d800000, v59
	v_exp_f32_e32 v62, v62
	v_sub_f32_e32 v63, v60, v58
	v_mul_f32_e32 v63, 0x3fb8aa3b, v63
	v_exp_f32_e32 v63, v63
	v_lshlrev_b32_e32 v59, 16, v7
	v_mul_f32_e32 v62, v62, v59
	v_cvt_pk_bf16_f32 v62, v62, v1
	ds_write_b16 v64, v62 offset:33280
	v_mul_f32_e32 v62, v63, v59
	v_cvt_pk_bf16_f32 v62, v62, v1
	ds_write_b16 v64, v62 offset:42496
	s_and_saveexec_b64 s[14:15], s[38:39]
	s_cbranch_execz .LBB0_148
	v_mul_f32_e32 v61, 0x3fb8aa3b, v61
	s_ashr_i32 s23, s22, 31
	v_exp_f32_e32 v61, v61
	s_lshl_b64 s[6:7], s[22:23], 2
	v_mul_f32_e32 v60, 0x3fb8aa3b, v60
	s_add_u32 s30, s18, s6
	v_exp_f32_e32 v60, v60
	s_addc_u32 s31, s21, s7
	s_add_u32 s6, s51, s6
	s_addc_u32 s7, s92, s7
	global_store_dword v1, v61, s[30:31] offset:8
	global_store_dword v1, v60, s[6:7] offset:8
; #define LAS __attribute__((address_space(3)))
; __device__ __forceinline__ float bflo(unsigned w) { return __uint_as_float(w << 16); }
; __device__ __forceinline__ float bfhi(unsigned w) { return __uint_as_float(w & 0xffff0000u); }
; __device__ __forceinline__ unsigned short f2bf(float f) { return (unsigned short)(cvt_pk_bf16(f, 0.f) & 0xffffu); }
; __device__ __forceinline__ float logsig(float x) { return fminf(x, 0.f) - __logf(1.f + __expf(-fabsf(x))); }
; __device__ __forceinline__ float wave_incl_scan(float x, int lane) {
; #pragma unroll
;     for (int o = 1; o < 64; o <<= 1) { const float t = __shfl_up(x, o); if (lane >= o) x += t; }
;     return x;
; }
; __device__ __forceinline__ void gla_p1(CArgs& a, int l, int cc, int h, LAS float* L, int dup, bool stagew) {
;     ...
;     for (int dd = 0; dd < 8; ++dd) { const int d = 8 * wid + dd;
;         float pf = L[GL_BF + d], pb = L[GL_BB + d];
; #pragma unroll
;         for (int q = 0; q < 4; ++q) { const f32x4 wf4 = *(const LAS f32x4*)(L + GL_WF + d * 16 + 4 * q), wb4 = *(const LAS f32x4*)(L + GL_WB + d * 16 + 4 * q);
; #pragma unroll
;             for (int e = 0; e < 4; ++e) { pf += cgf[4 * q + e] * wf4[e]; pb += cgb[4 * q + e] * wb4[e]; } }
;         const float gf = logsig(pf) * (1.f / 16.f), gb = logsig(pb) * (1.f / 16.f);
;         const float cf = wave_incl_scan(gf, lane), pbi = wave_incl_scan(gb, lane);
;         const float totf = __shfl(cf, 63), totb = __shfl(pbi, 63);
;         const float cb = totb - pbi + gb;
;         const float k = (dd & 1) ? bfhi(kw[dd >> 1]) : bflo(kw[dd >> 1]), q = ((dd & 1) ? bfhi(qw[dd >> 1]) : bflo(qw[dd >> 1])) * 0.125f;
;         oqf[dd] = q * __expf(cf); oqb[dd] = q * __expf(cb); okf[dd] = k * __expf(-cf); okb[dd] = k * __expf(-cb);
;         *(LAS unsigned short*)(B + GB_QDF + (d * HS + lane) * 2) = f2bf(k * __expf(totf - cf));
;         *(LAS unsigned short*)(B + GB_QDB + (d * HS + lane) * 2) = f2bf(k * __expf(totb - cb));
;         if (lane == 0) { DEC[(size_t)slot * 64 + d] = __expf(totf); DEC[(size_t)(slot + 1) * 64 + d] = __expf(totb); } }
.LBB0_148:
	s_or_b64 exec, exec, s[14:15]
	s_add_i32 s6, s4, 0x24e0c
	v_mov_b32_e32 v60, s6
	s_add_i32 s6, s4, 0x24f0c
	v_mov_b32_e32 v61, s6
	s_add_i32 s6, s5, 0x22ec0
	v_mov_b32_e32 v72, s6
	ds_read_b32 v92, v60
	ds_read_b32 v93, v61
	ds_read_b128 v[60:63], v72
	ds_read_b128 v[64:67], v72 offset:16
	ds_read_b128 v[68:71], v72 offset:32
	s_add_i32 s7, s5, 0x23ec0
	v_mov_b32_e32 v88, s7
	s_waitcnt lgkmcnt(2)
	v_fmac_f32_e32 v92, v60, v50
	v_fmac_f32_e32 v92, v61, v47
	v_fmac_f32_e32 v92, v62, v45
	v_fmac_f32_e32 v92, v63, v43
	s_waitcnt lgkmcnt(1)
	v_fmac_f32_e32 v92, v64, v41
	v_fmac_f32_e32 v92, v65, v39
	v_fmac_f32_e32 v92, v66, v37
	v_fmac_f32_e32 v92, v67, v35
	ds_read_b128 v[72:75], v72 offset:48
	ds_read_b128 v[76:79], v88
	s_waitcnt lgkmcnt(2)
	v_fmac_f32_e32 v92, v68, v33
	v_fmac_f32_e32 v92, v69, v31
	v_fmac_f32_e32 v92, v70, v29
	v_fmac_f32_e32 v92, v71, v28
	s_waitcnt lgkmcnt(1)
	v_fmac_f32_e32 v92, v72, v27
	s_waitcnt lgkmcnt(0)
	v_fmac_f32_e32 v93, v76, v49
	v_fmac_f32_e32 v92, v73, v26
	ds_read_b128 v[80:83], v88 offset:16
	ds_read_b128 v[84:87], v88 offset:32
	ds_read_b128 v[88:91], v88 offset:48
	v_fmac_f32_e32 v93, v77, v48
	v_fmac_f32_e32 v92, v74, v25
	v_fmac_f32_e32 v93, v78, v46
	v_fmac_f32_e32 v92, v75, v24
	v_fmac_f32_e32 v93, v79, v44
	v_mul_f32_e64 v60, |v92|, s27
	s_waitcnt lgkmcnt(2)
	v_fmac_f32_e32 v93, v80, v42
	v_exp_f32_e32 v60, v60
	v_fmac_f32_e32 v93, v81, v40
	v_fmac_f32_e32 v93, v82, v38
	v_fmac_f32_e32 v93, v83, v36
	s_waitcnt lgkmcnt(1)
	v_fmac_f32_e32 v93, v84, v34
	v_add_f32_e32 v60, 1.0, v60
	v_fmac_f32_e32 v93, v85, v32
	v_cmp_gt_f32_e64 s[52:53], s26, v60
	v_fmac_f32_e32 v93, v86, v30
	v_fmac_f32_e32 v93, v87, v19
	v_cndmask_b32_e64 v61, 0, 32, s[52:53]
	v_ldexp_f32 v60, v60, v61
	s_waitcnt lgkmcnt(0)
	v_fmac_f32_e32 v93, v88, v20
	v_log_f32_e32 v60, v60
	v_fmac_f32_e32 v93, v89, v21
	v_fmac_f32_e32 v93, v90, v17
	v_fmac_f32_e32 v93, v91, v18
	v_mul_f32_e32 v62, 0x3f317217, v60
	v_mul_f32_e64 v63, |v93|, s27
	v_fma_f32 v62, v60, s79, -v62
	v_exp_f32_e32 v63, v63
	v_fmac_f32_e32 v62, 0x3377d1cf, v60
	v_fmac_f32_e32 v62, 0x3f317217, v60
	v_cmp_lt_f32_e64 s[54:55], |v60|, s80
	v_min_f32_e32 v61, 0, v92
	v_add_u32_e32 v6, 0x48, v6
	v_cndmask_b32_e64 v60, v60, v62, s[54:55]
	v_cndmask_b32_e64 v62, 0, v225, s[52:53]
	v_sub_f32_e32 v60, v60, v62
	v_add_f32_e32 v62, 1.0, v63
	v_cmp_gt_f32_e64 s[52:53], s26, v62
	v_sub_f32_e32 v60, v61, v60
	v_mul_f32_e32 v61, 0x3d800000, v60
	v_cndmask_b32_e64 v63, 0, 32, s[52:53]
	v_ldexp_f32 v62, v62, v63
	v_log_f32_e32 v62, v62
	v_min_f32_e32 v63, 0, v93
	v_lshl_add_u32 v66, v6, 1, 0
	v_mul_f32_e32 v64, 0x3f317217, v62
	v_fma_f32 v64, v62, s79, -v64
	v_fmac_f32_e32 v64, 0x3377d1cf, v62
	v_fmac_f32_e32 v64, 0x3f317217, v62
	v_cmp_lt_f32_e64 s[54:55], |v62|, s80
	s_nop 1
	v_cndmask_b32_e64 v62, v62, v64, s[54:55]
	v_cndmask_b32_e64 v64, 0, v225, s[52:53]
	v_sub_f32_e32 v62, v62, v64
	v_sub_f32_e32 v62, v63, v62
	v_mul_f32_e32 v63, 0x3d800000, v62
	v_mov_b32_e32 v60, v61
	v_mov_b32_e32 v61, v63
	s_nop 1
	v_add_f32_dpp v60, v60, v60 row_shr:1 row_mask:0xf bank_mask:0xf
	v_add_f32_dpp v61, v61, v61 row_shr:1 row_mask:0xf bank_mask:0xf
	s_nop 0
	v_add_f32_dpp v60, v60, v60 row_shr:2 row_mask:0xf bank_mask:0xf
	v_add_f32_dpp v61, v61, v61 row_shr:2 row_mask:0xf bank_mask:0xf
	s_nop 0
	v_add_f32_dpp v60, v60, v60 row_shr:4 row_mask:0xf bank_mask:0xf
	v_add_f32_dpp v61, v61, v61 row_shr:4 row_mask:0xf bank_mask:0xf
	s_nop 0
	v_add_f32_dpp v60, v60, v60 row_shr:8 row_mask:0xf bank_mask:0xf
	v_add_f32_dpp v61, v61, v61 row_shr:8 row_mask:0xf bank_mask:0xf
	s_nop 0
	v_add_f32_dpp v60, v60, v60 row_bcast:15 row_mask:0xa bank_mask:0xf
	v_add_f32_dpp v61, v61, v61 row_bcast:15 row_mask:0xa bank_mask:0xf
	s_nop 0
	v_add_f32_dpp v60, v60, v60 row_bcast:31 row_mask:0xc bank_mask:0xf
	v_add_f32_dpp v61, v61, v61 row_bcast:31 row_mask:0xc bank_mask:0xf
	s_nop 0
	v_readlane_b32 s98, v60, 63
	v_readlane_b32 s99, v61, 63
	s_nop 1
	v_mov_b32_e32 v64, s98
	v_mov_b32_e32 v63, s99
	s_waitcnt lgkmcnt(1)
	v_sub_f32_e32 v65, v64, v60
	v_mul_f32_e32 v65, 0x3fb8aa3b, v65
	v_exp_f32_e32 v65, v65
	s_waitcnt lgkmcnt(0)
	v_sub_f32_e32 v61, v63, v61
	v_fmac_f32_e32 v61, 0x3d800000, v62
	v_and_b32_e32 v62, 0xffff0000, v7
	v_mul_f32_e32 v7, v65, v62
	v_sub_f32_e32 v65, v63, v61
	v_mul_f32_e32 v65, 0x3fb8aa3b, v65
	v_exp_f32_e32 v65, v65
	v_cvt_pk_bf16_f32 v7, v7, v1
	ds_write_b16 v66, v7 offset:33280
	v_mul_f32_e32 v7, v65, v62
	v_cvt_pk_bf16_f32 v7, v7, v1
	ds_write_b16 v66, v7 offset:42496
	s_and_saveexec_b64 s[14:15], s[38:39]
	s_cbranch_execz .LBB0_150
	v_mul_f32_e32 v7, 0x3fb8aa3b, v64
	s_ashr_i32 s23, s22, 31
	v_exp_f32_e32 v7, v7
	s_lshl_b64 s[6:7], s[22:23], 2
	v_mul_f32_e32 v63, 0x3fb8aa3b, v63
	s_add_u32 s30, s18, s6
	v_exp_f32_e32 v63, v63
	s_addc_u32 s31, s21, s7
	s_add_u32 s6, s51, s6
	s_addc_u32 s7, s92, s7
	global_store_dword v1, v7, s[30:31] offset:12
	global_store_dword v1, v63, s[6:7] offset:12
; #define LAS __attribute__((address_space(3)))
; __device__ __forceinline__ float bflo(unsigned w) { return __uint_as_float(w << 16); }
; __device__ __forceinline__ float bfhi(unsigned w) { return __uint_as_float(w & 0xffff0000u); }
; __device__ __forceinline__ unsigned short f2bf(float f) { return (unsigned short)(cvt_pk_bf16(f, 0.f) & 0xffffu); }
; __device__ __forceinline__ float logsig(float x) { return fminf(x, 0.f) - __logf(1.f + __expf(-fabsf(x))); }
; __device__ __forceinline__ float wave_incl_scan(float x, int lane) {
; #pragma unroll
;     for (int o = 1; o < 64; o <<= 1) { const float t = __shfl_up(x, o); if (lane >= o) x += t; }
;     return x;
; }
; __device__ __forceinline__ void gla_p1(CArgs& a, int l, int cc, int h, LAS float* L, int dup, bool stagew) {
;     ...
;     for (int dd = 0; dd < 8; ++dd) { const int d = 8 * wid + dd;
;         float pf = L[GL_BF + d], pb = L[GL_BB + d];
; #pragma unroll
;         for (int q = 0; q < 4; ++q) { const f32x4 wf4 = *(const LAS f32x4*)(L + GL_WF + d * 16 + 4 * q), wb4 = *(const LAS f32x4*)(L + GL_WB + d * 16 + 4 * q);
; #pragma unroll
;             for (int e = 0; e < 4; ++e) { pf += cgf[4 * q + e] * wf4[e]; pb += cgb[4 * q + e] * wb4[e]; } }
;         const float gf = logsig(pf) * (1.f / 16.f), gb = logsig(pb) * (1.f / 16.f);
;         const float cf = wave_incl_scan(gf, lane), pbi = wave_incl_scan(gb, lane);
;         const float totf = __shfl(cf, 63), totb = __shfl(pbi, 63);
;         const float cb = totb - pbi + gb;
;         const float k = (dd & 1) ? bfhi(kw[dd >> 1]) : bflo(kw[dd >> 1]), q = ((dd & 1) ? bfhi(qw[dd >> 1]) : bflo(qw[dd >> 1])) * 0.125f;
;         oqf[dd] = q * __expf(cf); oqb[dd] = q * __expf(cb); okf[dd] = k * __expf(-cf); okb[dd] = k * __expf(-cb);
;         *(LAS unsigned short*)(B + GB_QDF + (d * HS + lane) * 2) = f2bf(k * __expf(totf - cf));
;         *(LAS unsigned short*)(B + GB_QDB + (d * HS + lane) * 2) = f2bf(k * __expf(totb - cb));
;         if (lane == 0) { DEC[(size_t)slot * 64 + d] = __expf(totf); DEC[(size_t)(slot + 1) * 64 + d] = __expf(totb); } }
.LBB0_150:
	s_or_b64 exec, exec, s[14:15]
	s_add_i32 s6, s4, 0x24e10
	v_mov_b32_e32 v7, s6
	s_add_i32 s6, s4, 0x24f10
	v_mov_b32_e32 v63, s6
	s_add_i32 s6, s5, 0x22f00
	v_mov_b32_e32 v76, s6
	ds_read_b32 v7, v7
	ds_read_b32 v63, v63
	ds_read_b128 v[64:67], v76
	ds_read_b128 v[68:71], v76 offset:16
	ds_read_b128 v[72:75], v76 offset:32
	s_add_i32 s7, s5, 0x23f00
	v_mov_b32_e32 v92, s7
	s_waitcnt lgkmcnt(2)
	v_fmac_f32_e32 v7, v64, v50
	v_fmac_f32_e32 v7, v65, v47
	v_fmac_f32_e32 v7, v66, v45
	v_fmac_f32_e32 v7, v67, v43
	s_waitcnt lgkmcnt(1)
	v_fmac_f32_e32 v7, v68, v41
	v_fmac_f32_e32 v7, v69, v39
	v_fmac_f32_e32 v7, v70, v37
	v_fmac_f32_e32 v7, v71, v35
	ds_read_b128 v[76:79], v76 offset:48
	ds_read_b128 v[80:83], v92
	s_waitcnt lgkmcnt(2)
	v_fmac_f32_e32 v7, v72, v33
	v_fmac_f32_e32 v7, v73, v31
	v_fmac_f32_e32 v7, v74, v29
	v_fmac_f32_e32 v7, v75, v28
	s_waitcnt lgkmcnt(1)
	v_fmac_f32_e32 v7, v76, v27
	s_waitcnt lgkmcnt(0)
	v_fmac_f32_e32 v63, v80, v49
	v_fmac_f32_e32 v7, v77, v26
	ds_read_b128 v[84:87], v92 offset:16
	ds_read_b128 v[88:91], v92 offset:32
	ds_read_b128 v[92:95], v92 offset:48
	v_fmac_f32_e32 v63, v81, v48
	v_fmac_f32_e32 v7, v78, v25
	v_fmac_f32_e32 v63, v82, v46
	v_fmac_f32_e32 v7, v79, v24
	v_fmac_f32_e32 v63, v83, v44
	v_mul_f32_e64 v64, |v7|, s27
	s_waitcnt lgkmcnt(2)
	v_fmac_f32_e32 v63, v84, v42
	v_exp_f32_e32 v64, v64
	v_fmac_f32_e32 v63, v85, v40
	v_fmac_f32_e32 v63, v86, v38
	v_fmac_f32_e32 v63, v87, v36
	s_waitcnt lgkmcnt(1)
	v_fmac_f32_e32 v63, v88, v34
	v_add_f32_e32 v64, 1.0, v64
	v_fmac_f32_e32 v63, v89, v32
	v_cmp_gt_f32_e64 s[52:53], s26, v64
	v_fmac_f32_e32 v63, v90, v30
	v_fmac_f32_e32 v63, v91, v19
	v_cndmask_b32_e64 v65, 0, 32, s[52:53]
	v_ldexp_f32 v64, v64, v65
	s_waitcnt lgkmcnt(0)
	v_fmac_f32_e32 v63, v92, v20
	v_log_f32_e32 v64, v64
	v_fmac_f32_e32 v63, v93, v21
	v_fmac_f32_e32 v63, v94, v17
	v_fmac_f32_e32 v63, v95, v18
	v_mul_f32_e32 v65, 0x3f317217, v64
	v_mul_f32_e64 v66, |v63|, s27
	v_fma_f32 v65, v64, s79, -v65
	v_exp_f32_e32 v66, v66
	v_fmac_f32_e32 v65, 0x3377d1cf, v64
	v_fmac_f32_e32 v65, 0x3f317217, v64
	v_cmp_lt_f32_e64 s[54:55], |v64|, s80
	v_min_f32_e32 v7, 0, v7
	v_min_f32_e32 v63, 0, v63
	v_cndmask_b32_e64 v64, v64, v65, s[54:55]
	v_cndmask_b32_e64 v65, 0, v225, s[52:53]
	v_sub_f32_e32 v64, v64, v65
	v_add_f32_e32 v65, 1.0, v66
	v_cmp_gt_f32_e64 s[52:53], s26, v65
	v_sub_f32_e32 v7, v7, v64
	v_mul_f32_e32 v64, 0x3d800000, v7
	v_cndmask_b32_e64 v66, 0, 32, s[52:53]
	v_ldexp_f32 v65, v65, v66
	v_log_f32_e32 v65, v65
	v_add_u32_e32 v6, 0x48, v6
	v_lshl_add_u32 v69, v6, 1, 0
	v_mul_f32_e32 v66, 0x3f317217, v65
	v_fma_f32 v66, v65, s79, -v66
	v_fmac_f32_e32 v66, 0x3377d1cf, v65
	v_fmac_f32_e32 v66, 0x3f317217, v65
	v_cmp_lt_f32_e64 s[54:55], |v65|, s80
	s_nop 1
	v_cndmask_b32_e64 v65, v65, v66, s[54:55]
	v_cndmask_b32_e64 v66, 0, v225, s[52:53]
	v_sub_f32_e32 v65, v65, v66
	v_sub_f32_e32 v65, v63, v65
	v_mul_f32_e32 v63, 0x3d800000, v65
	v_mov_b32_e32 v66, v64
	v_mov_b32_e32 v64, v63
	v_mov_b32_e32 v63, v66
	s_nop 1
	v_add_f32_dpp v63, v63, v63 row_shr:1 row_mask:0xf bank_mask:0xf
	v_add_f32_dpp v64, v64, v64 row_shr:1 row_mask:0xf bank_mask:0xf
	s_nop 0
	v_add_f32_dpp v63, v63, v63 row_shr:2 row_mask:0xf bank_mask:0xf
	v_add_f32_dpp v64, v64, v64 row_shr:2 row_mask:0xf bank_mask:0xf
	s_nop 0
	v_add_f32_dpp v63, v63, v63 row_shr:4 row_mask:0xf bank_mask:0xf
	v_add_f32_dpp v64, v64, v64 row_shr:4 row_mask:0xf bank_mask:0xf
	s_nop 0
	v_add_f32_dpp v63, v63, v63 row_shr:8 row_mask:0xf bank_mask:0xf
	v_add_f32_dpp v64, v64, v64 row_shr:8 row_mask:0xf bank_mask:0xf
	s_nop 0
	v_add_f32_dpp v63, v63, v63 row_bcast:15 row_mask:0xa bank_mask:0xf
	v_add_f32_dpp v64, v64, v64 row_bcast:15 row_mask:0xa bank_mask:0xf
	s_nop 0
	v_add_f32_dpp v63, v63, v63 row_bcast:31 row_mask:0xc bank_mask:0xf
	v_add_f32_dpp v64, v64, v64 row_bcast:31 row_mask:0xc bank_mask:0xf
	s_nop 0
	v_readlane_b32 s98, v63, 63
	v_readlane_b32 s99, v64, 63
	s_nop 1
	v_mov_b32_e32 v66, s98
	v_mov_b32_e32 v7, s99
	s_waitcnt lgkmcnt(1)
	v_sub_f32_e32 v67, v66, v63
	s_waitcnt lgkmcnt(0)
	v_sub_f32_e32 v64, v7, v64
	v_mul_f32_e32 v67, 0x3fb8aa3b, v67
	v_fmac_f32_e32 v64, 0x3d800000, v65
	v_exp_f32_e32 v67, v67
	v_sub_f32_e32 v68, v7, v64
	v_mul_f32_e32 v68, 0x3fb8aa3b, v68
	v_exp_f32_e32 v68, v68
	v_lshlrev_b32_e32 v65, 16, v8
	v_mul_f32_e32 v67, v67, v65
	v_cvt_pk_bf16_f32 v67, v67, v1
	ds_write_b16 v69, v67 offset:33280
	v_mul_f32_e32 v67, v68, v65
	v_cvt_pk_bf16_f32 v67, v67, v1
	ds_write_b16 v69, v67 offset:42496
	s_and_saveexec_b64 s[14:15], s[38:39]
	s_cbranch_execz .LBB0_152
	v_mul_f32_e32 v66, 0x3fb8aa3b, v66
	s_ashr_i32 s23, s22, 31
	v_exp_f32_e32 v66, v66
	s_lshl_b64 s[6:7], s[22:23], 2
	v_mul_f32_e32 v7, 0x3fb8aa3b, v7
	s_add_u32 s30, s18, s6
	v_exp_f32_e32 v7, v7
	s_addc_u32 s31, s21, s7
	s_add_u32 s6, s51, s6
	s_addc_u32 s7, s92, s7
	global_store_dword v1, v66, s[30:31] offset:16
	global_store_dword v1, v7, s[6:7] offset:16
; #define LAS __attribute__((address_space(3)))
; __device__ __forceinline__ float bflo(unsigned w) { return __uint_as_float(w << 16); }
; __device__ __forceinline__ float bfhi(unsigned w) { return __uint_as_float(w & 0xffff0000u); }
; __device__ __forceinline__ unsigned short f2bf(float f) { return (unsigned short)(cvt_pk_bf16(f, 0.f) & 0xffffu); }
; __device__ __forceinline__ float logsig(float x) { return fminf(x, 0.f) - __logf(1.f + __expf(-fabsf(x))); }
; __device__ __forceinline__ float wave_incl_scan(float x, int lane) {
; #pragma unroll
;     for (int o = 1; o < 64; o <<= 1) { const float t = __shfl_up(x, o); if (lane >= o) x += t; }
;     return x;
; }
; __device__ __forceinline__ void gla_p1(CArgs& a, int l, int cc, int h, LAS float* L, int dup, bool stagew) {
;     ...
;     for (int dd = 0; dd < 8; ++dd) { const int d = 8 * wid + dd;
;         float pf = L[GL_BF + d], pb = L[GL_BB + d];
; #pragma unroll
;         for (int q = 0; q < 4; ++q) { const f32x4 wf4 = *(const LAS f32x4*)(L + GL_WF + d * 16 + 4 * q), wb4 = *(const LAS f32x4*)(L + GL_WB + d * 16 + 4 * q);
; #pragma unroll
;             for (int e = 0; e < 4; ++e) { pf += cgf[4 * q + e] * wf4[e]; pb += cgb[4 * q + e] * wb4[e]; } }
;         const float gf = logsig(pf) * (1.f / 16.f), gb = logsig(pb) * (1.f / 16.f);
;         const float cf = wave_incl_scan(gf, lane), pbi = wave_incl_scan(gb, lane);
;         const float totf = __shfl(cf, 63), totb = __shfl(pbi, 63);
;         const float cb = totb - pbi + gb;
;         const float k = (dd & 1) ? bfhi(kw[dd >> 1]) : bflo(kw[dd >> 1]), q = ((dd & 1) ? bfhi(qw[dd >> 1]) : bflo(qw[dd >> 1])) * 0.125f;
;         oqf[dd] = q * __expf(cf); oqb[dd] = q * __expf(cb); okf[dd] = k * __expf(-cf); okb[dd] = k * __expf(-cb);
;         *(LAS unsigned short*)(B + GB_QDF + (d * HS + lane) * 2) = f2bf(k * __expf(totf - cf));
;         *(LAS unsigned short*)(B + GB_QDB + (d * HS + lane) * 2) = f2bf(k * __expf(totb - cb));
;         if (lane == 0) { DEC[(size_t)slot * 64 + d] = __expf(totf); DEC[(size_t)(slot + 1) * 64 + d] = __expf(totb); } }
.LBB0_152:
	s_or_b64 exec, exec, s[14:15]
	s_add_i32 s6, s4, 0x24e14
	v_mov_b32_e32 v7, s6
	s_add_i32 s6, s4, 0x24f14
	v_mov_b32_e32 v66, s6
	s_add_i32 s6, s5, 0x22f40
	v_mov_b32_e32 v78, s6
	ds_read_b32 v7, v7
	ds_read_b32 v98, v66
	ds_read_b128 v[66:69], v78
	ds_read_b128 v[70:73], v78 offset:16
	ds_read_b128 v[74:77], v78 offset:32
	s_add_i32 s7, s5, 0x23f40
	v_mov_b32_e32 v94, s7
	s_waitcnt lgkmcnt(2)
	v_fmac_f32_e32 v7, v66, v50
	v_fmac_f32_e32 v7, v67, v47
	v_fmac_f32_e32 v7, v68, v45
	v_fmac_f32_e32 v7, v69, v43
	s_waitcnt lgkmcnt(1)
	v_fmac_f32_e32 v7, v70, v41
	v_fmac_f32_e32 v7, v71, v39
	v_fmac_f32_e32 v7, v72, v37
	v_fmac_f32_e32 v7, v73, v35
	ds_read_b128 v[78:81], v78 offset:48
	ds_read_b128 v[82:85], v94
	s_waitcnt lgkmcnt(2)
	v_fmac_f32_e32 v7, v74, v33
	v_fmac_f32_e32 v7, v75, v31
	v_fmac_f32_e32 v7, v76, v29
	v_fmac_f32_e32 v7, v77, v28
	s_waitcnt lgkmcnt(1)
	v_fmac_f32_e32 v7, v78, v27
	s_waitcnt lgkmcnt(0)
	v_fmac_f32_e32 v98, v82, v49
	v_fmac_f32_e32 v7, v79, v26
	ds_read_b128 v[86:89], v94 offset:16
	ds_read_b128 v[90:93], v94 offset:32
	ds_read_b128 v[94:97], v94 offset:48
	v_fmac_f32_e32 v98, v83, v48
	v_fmac_f32_e32 v7, v80, v25
	v_fmac_f32_e32 v98, v84, v46
	v_fmac_f32_e32 v7, v81, v24
	v_fmac_f32_e32 v98, v85, v44
	v_mul_f32_e64 v66, |v7|, s27
	s_waitcnt lgkmcnt(2)
	v_fmac_f32_e32 v98, v86, v42
	v_exp_f32_e32 v66, v66
	v_fmac_f32_e32 v98, v87, v40
	v_fmac_f32_e32 v98, v88, v38
	v_fmac_f32_e32 v98, v89, v36
	s_waitcnt lgkmcnt(1)
	v_fmac_f32_e32 v98, v90, v34
	v_add_f32_e32 v66, 1.0, v66
	v_fmac_f32_e32 v98, v91, v32
	v_cmp_gt_f32_e64 s[52:53], s26, v66
	v_fmac_f32_e32 v98, v92, v30
	v_fmac_f32_e32 v98, v93, v19
	v_cndmask_b32_e64 v67, 0, 32, s[52:53]
	v_ldexp_f32 v66, v66, v67
	s_waitcnt lgkmcnt(0)
	v_fmac_f32_e32 v98, v94, v20
	v_log_f32_e32 v66, v66
	v_fmac_f32_e32 v98, v95, v21
	v_fmac_f32_e32 v98, v96, v17
	v_fmac_f32_e32 v98, v97, v18
	v_mul_f32_e32 v67, 0x3f317217, v66
	v_mul_f32_e64 v68, |v98|, s27
	v_fma_f32 v67, v66, s79, -v67
	v_exp_f32_e32 v68, v68
	v_fmac_f32_e32 v67, 0x3377d1cf, v66
	v_fmac_f32_e32 v67, 0x3f317217, v66
	v_cmp_lt_f32_e64 s[54:55], |v66|, s80
	v_min_f32_e32 v7, 0, v7
	v_and_b32_e32 v8, 0xffff0000, v8
	v_cndmask_b32_e64 v66, v66, v67, s[54:55]
	v_cndmask_b32_e64 v67, 0, v225, s[52:53]
	v_sub_f32_e32 v66, v66, v67
	v_add_f32_e32 v67, 1.0, v68
	v_cmp_gt_f32_e64 s[52:53], s26, v67
	v_sub_f32_e32 v7, v7, v66
	v_mul_f32_e32 v66, 0x3d800000, v7
	v_cndmask_b32_e64 v68, 0, 32, s[52:53]
	v_ldexp_f32 v67, v67, v68
	v_log_f32_e32 v67, v67
	v_min_f32_e32 v68, 0, v98
	v_add_u32_e32 v6, 0x48, v6
	v_lshl_add_u32 v71, v6, 1, 0
	v_mul_f32_e32 v69, 0x3f317217, v67
	v_fma_f32 v69, v67, s79, -v69
	v_fmac_f32_e32 v69, 0x3377d1cf, v67
	v_fmac_f32_e32 v69, 0x3f317217, v67
	v_cmp_lt_f32_e64 s[54:55], |v67|, s80
	s_nop 1
	v_cndmask_b32_e64 v67, v67, v69, s[54:55]
	v_cndmask_b32_e64 v69, 0, v225, s[52:53]
	v_sub_f32_e32 v67, v67, v69
	v_sub_f32_e32 v70, v68, v67
	v_mul_f32_e32 v67, 0x3d800000, v70
	s_nop 1
	v_add_f32_dpp v66, v66, v66 row_shr:1 row_mask:0xf bank_mask:0xf
	v_add_f32_dpp v67, v67, v67 row_shr:1 row_mask:0xf bank_mask:0xf
	s_nop 0
	v_add_f32_dpp v66, v66, v66 row_shr:2 row_mask:0xf bank_mask:0xf
	v_add_f32_dpp v67, v67, v67 row_shr:2 row_mask:0xf bank_mask:0xf
	s_nop 0
	v_add_f32_dpp v66, v66, v66 row_shr:4 row_mask:0xf bank_mask:0xf
	v_add_f32_dpp v67, v67, v67 row_shr:4 row_mask:0xf bank_mask:0xf
	s_nop 0
	v_add_f32_dpp v66, v66, v66 row_shr:8 row_mask:0xf bank_mask:0xf
	v_add_f32_dpp v67, v67, v67 row_shr:8 row_mask:0xf bank_mask:0xf
	s_nop 0
	v_add_f32_dpp v66, v66, v66 row_bcast:15 row_mask:0xa bank_mask:0xf
	v_add_f32_dpp v67, v67, v67 row_bcast:15 row_mask:0xa bank_mask:0xf
	s_nop 0
	v_add_f32_dpp v66, v66, v66 row_bcast:31 row_mask:0xc bank_mask:0xf
	v_add_f32_dpp v67, v67, v67 row_bcast:31 row_mask:0xc bank_mask:0xf
	s_nop 0
	v_readlane_b32 s98, v66, 63
	v_readlane_b32 s99, v67, 63
	s_nop 1
	v_mov_b32_e32 v68, s98
	v_mov_b32_e32 v7, s99
	s_waitcnt lgkmcnt(1)
	v_sub_f32_e32 v69, v68, v66
	s_waitcnt lgkmcnt(0)
	v_sub_f32_e32 v67, v7, v67
	v_mul_f32_e32 v69, 0x3fb8aa3b, v69
	v_fmac_f32_e32 v67, 0x3d800000, v70
	v_exp_f32_e32 v69, v69
	v_sub_f32_e32 v70, v7, v67
	v_mul_f32_e32 v70, 0x3fb8aa3b, v70
	v_exp_f32_e32 v70, v70
	v_mul_f32_e32 v69, v69, v8
	v_cvt_pk_bf16_f32 v69, v69, v1
	ds_write_b16 v71, v69 offset:33280
	v_mul_f32_e32 v69, v70, v8
	v_cvt_pk_bf16_f32 v69, v69, v1
	ds_write_b16 v71, v69 offset:42496
	s_and_saveexec_b64 s[14:15], s[38:39]
	s_cbranch_execz .LBB0_154
	v_mul_f32_e32 v68, 0x3fb8aa3b, v68
	s_ashr_i32 s23, s22, 31
	v_exp_f32_e32 v68, v68
	s_lshl_b64 s[6:7], s[22:23], 2
	v_mul_f32_e32 v7, 0x3fb8aa3b, v7
	s_add_u32 s30, s18, s6
	v_exp_f32_e32 v7, v7
	s_addc_u32 s31, s21, s7
	s_add_u32 s6, s51, s6
	s_addc_u32 s7, s92, s7
	global_store_dword v1, v68, s[30:31] offset:20
	global_store_dword v1, v7, s[6:7] offset:20
; #define LAS __attribute__((address_space(3)))
; __device__ __forceinline__ float bflo(unsigned w) { return __uint_as_float(w << 16); }
; __device__ __forceinline__ float bfhi(unsigned w) { return __uint_as_float(w & 0xffff0000u); }
; __device__ __forceinline__ unsigned short f2bf(float f) { return (unsigned short)(cvt_pk_bf16(f, 0.f) & 0xffffu); }
; __device__ __forceinline__ float logsig(float x) { return fminf(x, 0.f) - __logf(1.f + __expf(-fabsf(x))); }
; __device__ __forceinline__ float wave_incl_scan(float x, int lane) {
; #pragma unroll
;     for (int o = 1; o < 64; o <<= 1) { const float t = __shfl_up(x, o); if (lane >= o) x += t; }
;     return x;
; }
; __device__ __forceinline__ void gla_p1(CArgs& a, int l, int cc, int h, LAS float* L, int dup, bool stagew) {
;     ...
;     for (int dd = 0; dd < 8; ++dd) { const int d = 8 * wid + dd;
;         float pf = L[GL_BF + d], pb = L[GL_BB + d];
; #pragma unroll
;         for (int q = 0; q < 4; ++q) { const f32x4 wf4 = *(const LAS f32x4*)(L + GL_WF + d * 16 + 4 * q), wb4 = *(const LAS f32x4*)(L + GL_WB + d * 16 + 4 * q);
; #pragma unroll
;             for (int e = 0; e < 4; ++e) { pf += cgf[4 * q + e] * wf4[e]; pb += cgb[4 * q + e] * wb4[e]; } }
;         const float gf = logsig(pf) * (1.f / 16.f), gb = logsig(pb) * (1.f / 16.f);
;         const float cf = wave_incl_scan(gf, lane), pbi = wave_incl_scan(gb, lane);
;         const float totf = __shfl(cf, 63), totb = __shfl(pbi, 63);
;         const float cb = totb - pbi + gb;
;         const float k = (dd & 1) ? bfhi(kw[dd >> 1]) : bflo(kw[dd >> 1]), q = ((dd & 1) ? bfhi(qw[dd >> 1]) : bflo(qw[dd >> 1])) * 0.125f;
;         oqf[dd] = q * __expf(cf); oqb[dd] = q * __expf(cb); okf[dd] = k * __expf(-cf); okb[dd] = k * __expf(-cb);
;         *(LAS unsigned short*)(B + GB_QDF + (d * HS + lane) * 2) = f2bf(k * __expf(totf - cf));
;         *(LAS unsigned short*)(B + GB_QDB + (d * HS + lane) * 2) = f2bf(k * __expf(totb - cb));
;         if (lane == 0) { DEC[(size_t)slot * 64 + d] = __expf(totf); DEC[(size_t)(slot + 1) * 64 + d] = __expf(totb); } }
.LBB0_154:
	s_or_b64 exec, exec, s[14:15]
	s_add_i32 s6, s4, 0x24e18
	v_mov_b32_e32 v7, s6
	s_add_i32 s6, s4, 0x24f18
	v_mov_b32_e32 v68, s6
	s_add_i32 s6, s5, 0x22f80
	v_mov_b32_e32 v80, s6
	ds_read_b32 v7, v7
	ds_read_b32 v100, v68
	ds_read_b128 v[68:71], v80
	ds_read_b128 v[72:75], v80 offset:16
	ds_read_b128 v[76:79], v80 offset:32
	s_add_i32 s7, s5, 0x23f80
	v_mov_b32_e32 v96, s7
	s_waitcnt lgkmcnt(2)
	v_fmac_f32_e32 v7, v68, v50
	v_fmac_f32_e32 v7, v69, v47
	v_fmac_f32_e32 v7, v70, v45
	v_fmac_f32_e32 v7, v71, v43
	s_waitcnt lgkmcnt(1)
	v_fmac_f32_e32 v7, v72, v41
	v_fmac_f32_e32 v7, v73, v39
	v_fmac_f32_e32 v7, v74, v37
	v_fmac_f32_e32 v7, v75, v35
	ds_read_b128 v[80:83], v80 offset:48
	ds_read_b128 v[84:87], v96
	s_waitcnt lgkmcnt(2)
	v_fmac_f32_e32 v7, v76, v33
	v_fmac_f32_e32 v7, v77, v31
	v_fmac_f32_e32 v7, v78, v29
	v_fmac_f32_e32 v7, v79, v28
	s_waitcnt lgkmcnt(1)
	v_fmac_f32_e32 v7, v80, v27
	s_waitcnt lgkmcnt(0)
	v_fmac_f32_e32 v100, v84, v49
	v_fmac_f32_e32 v7, v81, v26
	ds_read_b128 v[88:91], v96 offset:16
	ds_read_b128 v[92:95], v96 offset:32
	ds_read_b128 v[96:99], v96 offset:48
	v_fmac_f32_e32 v100, v85, v48
	v_fmac_f32_e32 v7, v82, v25
	v_fmac_f32_e32 v100, v86, v46
	v_fmac_f32_e32 v7, v83, v24
	v_fmac_f32_e32 v100, v87, v44
	v_mul_f32_e64 v68, |v7|, s27
	s_waitcnt lgkmcnt(2)
	v_fmac_f32_e32 v100, v88, v42
	v_exp_f32_e32 v68, v68
	v_fmac_f32_e32 v100, v89, v40
	v_fmac_f32_e32 v100, v90, v38
	v_fmac_f32_e32 v100, v91, v36
	s_waitcnt lgkmcnt(1)
	v_fmac_f32_e32 v100, v92, v34
	v_add_f32_e32 v68, 1.0, v68
	v_fmac_f32_e32 v100, v93, v32
	v_cmp_gt_f32_e64 s[52:53], s26, v68
	v_fmac_f32_e32 v100, v94, v30
	v_fmac_f32_e32 v100, v95, v19
	v_cndmask_b32_e64 v69, 0, 32, s[52:53]
	v_ldexp_f32 v68, v68, v69
	s_waitcnt lgkmcnt(0)
	v_fmac_f32_e32 v100, v96, v20
	v_log_f32_e32 v68, v68
	v_fmac_f32_e32 v100, v97, v21
	v_fmac_f32_e32 v100, v98, v17
	v_fmac_f32_e32 v100, v99, v18
	v_mul_f32_e32 v69, 0x3f317217, v68
	v_mul_f32_e64 v70, |v100|, s27
	v_fma_f32 v69, v68, s79, -v69
	v_exp_f32_e32 v70, v70
	v_fmac_f32_e32 v69, 0x3377d1cf, v68
	v_fmac_f32_e32 v69, 0x3f317217, v68
	v_cmp_lt_f32_e64 s[54:55], |v68|, s80
	v_min_f32_e32 v7, 0, v7
	v_add_u32_e32 v6, 0x48, v6
	v_cndmask_b32_e64 v68, v68, v69, s[54:55]
	v_cndmask_b32_e64 v69, 0, v225, s[52:53]
	v_sub_f32_e32 v68, v68, v69
	v_add_f32_e32 v69, 1.0, v70
	v_cmp_gt_f32_e64 s[52:53], s26, v69
	v_sub_f32_e32 v7, v7, v68
	v_mul_f32_e32 v68, 0x3d800000, v7
	v_cndmask_b32_e64 v70, 0, 32, s[52:53]
	v_ldexp_f32 v69, v69, v70
	v_log_f32_e32 v69, v69
	v_min_f32_e32 v70, 0, v100
	v_lshl_add_u32 v6, v6, 1, 0
	v_mul_f32_e32 v71, 0x3f317217, v69
	v_fma_f32 v71, v69, s79, -v71
	v_fmac_f32_e32 v71, 0x3377d1cf, v69
	v_fmac_f32_e32 v71, 0x3f317217, v69
	v_cmp_lt_f32_e64 s[54:55], |v69|, s80
	s_nop 1
	v_cndmask_b32_e64 v69, v69, v71, s[54:55]
	v_cndmask_b32_e64 v71, 0, v225, s[52:53]
	v_sub_f32_e32 v69, v69, v71
	v_sub_f32_e32 v70, v70, v69
	v_mul_f32_e32 v69, 0x3d800000, v70
	s_nop 1
	v_add_f32_dpp v68, v68, v68 row_shr:1 row_mask:0xf bank_mask:0xf
	v_add_f32_dpp v69, v69, v69 row_shr:1 row_mask:0xf bank_mask:0xf
	s_nop 0
	v_add_f32_dpp v68, v68, v68 row_shr:2 row_mask:0xf bank_mask:0xf
	v_add_f32_dpp v69, v69, v69 row_shr:2 row_mask:0xf bank_mask:0xf
	s_nop 0
	v_add_f32_dpp v68, v68, v68 row_shr:4 row_mask:0xf bank_mask:0xf
	v_add_f32_dpp v69, v69, v69 row_shr:4 row_mask:0xf bank_mask:0xf
	s_nop 0
	v_add_f32_dpp v68, v68, v68 row_shr:8 row_mask:0xf bank_mask:0xf
	v_add_f32_dpp v69, v69, v69 row_shr:8 row_mask:0xf bank_mask:0xf
	s_nop 0
	v_add_f32_dpp v68, v68, v68 row_bcast:15 row_mask:0xa bank_mask:0xf
	v_add_f32_dpp v69, v69, v69 row_bcast:15 row_mask:0xa bank_mask:0xf
	s_nop 0
	v_add_f32_dpp v68, v68, v68 row_bcast:31 row_mask:0xc bank_mask:0xf
	v_add_f32_dpp v69, v69, v69 row_bcast:31 row_mask:0xc bank_mask:0xf
	s_nop 0
	v_readlane_b32 s98, v68, 63
	v_readlane_b32 s99, v69, 63
	s_nop 1
	v_mov_b32_e32 v71, s98
	v_mov_b32_e32 v7, s99
	s_waitcnt lgkmcnt(1)
	v_sub_f32_e32 v72, v71, v68
	s_waitcnt lgkmcnt(0)
	v_sub_f32_e32 v69, v7, v69
	v_mul_f32_e32 v72, 0x3fb8aa3b, v72
	v_fmac_f32_e32 v69, 0x3d800000, v70
	v_exp_f32_e32 v72, v72
	v_sub_f32_e32 v73, v7, v69
	v_mul_f32_e32 v73, 0x3fb8aa3b, v73
	v_exp_f32_e32 v73, v73
	v_lshlrev_b32_e32 v70, 16, v9
	v_mul_f32_e32 v72, v72, v70
	v_cvt_pk_bf16_f32 v72, v72, v1
	ds_write_b16 v6, v72 offset:33280
	v_mul_f32_e32 v72, v73, v70
	v_cvt_pk_bf16_f32 v72, v72, v1
	ds_write_b16 v6, v72 offset:42496
	s_and_saveexec_b64 s[14:15], s[38:39]
	s_cbranch_execz .LBB0_156
	v_mul_f32_e32 v71, 0x3fb8aa3b, v71
	s_ashr_i32 s23, s22, 31
	v_exp_f32_e32 v71, v71
	s_lshl_b64 s[6:7], s[22:23], 2
	v_mul_f32_e32 v7, 0x3fb8aa3b, v7
	s_add_u32 s30, s18, s6
	v_exp_f32_e32 v7, v7
	s_addc_u32 s31, s21, s7
	s_add_u32 s6, s51, s6
	s_addc_u32 s7, s92, s7
	global_store_dword v1, v71, s[30:31] offset:24
	global_store_dword v1, v7, s[6:7] offset:24
; #define LAS __attribute__((address_space(3)))
; __device__ __forceinline__ float bflo(unsigned w) { return __uint_as_float(w << 16); }
; __device__ __forceinline__ float bfhi(unsigned w) { return __uint_as_float(w & 0xffff0000u); }
; __device__ __forceinline__ unsigned short f2bf(float f) { return (unsigned short)(cvt_pk_bf16(f, 0.f) & 0xffffu); }
; __device__ __forceinline__ float logsig(float x) { return fminf(x, 0.f) - __logf(1.f + __expf(-fabsf(x))); }
; __device__ __forceinline__ float wave_incl_scan(float x, int lane) {
; #pragma unroll
;     for (int o = 1; o < 64; o <<= 1) { const float t = __shfl_up(x, o); if (lane >= o) x += t; }
;     return x;
; }
; __device__ __forceinline__ void gla_p1(CArgs& a, int l, int cc, int h, LAS float* L, int dup, bool stagew) {
;     ...
;     for (int dd = 0; dd < 8; ++dd) { const int d = 8 * wid + dd;
;         float pf = L[GL_BF + d], pb = L[GL_BB + d];
; #pragma unroll
;         for (int q = 0; q < 4; ++q) { const f32x4 wf4 = *(const LAS f32x4*)(L + GL_WF + d * 16 + 4 * q), wb4 = *(const LAS f32x4*)(L + GL_WB + d * 16 + 4 * q);
; #pragma unroll
;             for (int e = 0; e < 4; ++e) { pf += cgf[4 * q + e] * wf4[e]; pb += cgb[4 * q + e] * wb4[e]; } }
;         const float gf = logsig(pf) * (1.f / 16.f), gb = logsig(pb) * (1.f / 16.f);
;         const float cf = wave_incl_scan(gf, lane), pbi = wave_incl_scan(gb, lane);
;         const float totf = __shfl(cf, 63), totb = __shfl(pbi, 63);
;         const float cb = totb - pbi + gb;
;         const float k = (dd & 1) ? bfhi(kw[dd >> 1]) : bflo(kw[dd >> 1]), q = ((dd & 1) ? bfhi(qw[dd >> 1]) : bflo(qw[dd >> 1])) * 0.125f;
;         oqf[dd] = q * __expf(cf); oqb[dd] = q * __expf(cb); okf[dd] = k * __expf(-cf); okb[dd] = k * __expf(-cb);
;         *(LAS unsigned short*)(B + GB_QDF + (d * HS + lane) * 2) = f2bf(k * __expf(totf - cf));
;         *(LAS unsigned short*)(B + GB_QDB + (d * HS + lane) * 2) = f2bf(k * __expf(totb - cb));
;         if (lane == 0) { DEC[(size_t)slot * 64 + d] = __expf(totf); DEC[(size_t)(slot + 1) * 64 + d] = __expf(totb); } }
.LBB0_156:
	s_or_b64 exec, exec, s[14:15]
	s_add_i32 s6, s4, 0x24e1c
	s_add_i32 s4, s4, 0x24f1c
	v_mov_b32_e32 v7, s6
	v_mov_b32_e32 v71, s4
	s_add_i32 s4, s5, 0x22fc0
	v_mov_b32_e32 v84, s4
	ds_read_b32 v7, v7
	ds_read_b32 v71, v71
	ds_read_b128 v[72:75], v84
	ds_read_b128 v[76:79], v84 offset:16
	ds_read_b128 v[80:83], v84 offset:32
	s_add_i32 s5, s5, 0x23fc0
	v_mov_b32_e32 v100, s5
	s_waitcnt lgkmcnt(2)
	v_fmac_f32_e32 v7, v72, v50
	v_fmac_f32_e32 v7, v73, v47
	v_fmac_f32_e32 v7, v74, v45
	v_fmac_f32_e32 v7, v75, v43
	s_waitcnt lgkmcnt(1)
	v_fmac_f32_e32 v7, v76, v41
	ds_read_b128 v[84:87], v84 offset:48
	ds_read_b128 v[88:91], v100
	v_fmac_f32_e32 v7, v77, v39
	v_fmac_f32_e32 v7, v78, v37
	v_fmac_f32_e32 v7, v79, v35
	s_waitcnt lgkmcnt(2)
	v_fmac_f32_e32 v7, v80, v33
	v_fmac_f32_e32 v7, v81, v31
	s_waitcnt lgkmcnt(0)
	v_fmac_f32_e32 v71, v88, v49
	v_fmac_f32_e32 v7, v82, v29
	ds_read_b128 v[92:95], v100 offset:16
	ds_read_b128 v[96:99], v100 offset:32
	ds_read_b128 v[100:103], v100 offset:48
	v_fmac_f32_e32 v71, v89, v48
	v_fmac_f32_e32 v7, v83, v28
	v_fmac_f32_e32 v71, v90, v46
	v_fmac_f32_e32 v7, v84, v27
	v_fmac_f32_e32 v71, v91, v44
	v_fmac_f32_e32 v7, v85, v26
	s_waitcnt lgkmcnt(2)
	v_fmac_f32_e32 v71, v92, v42
	v_fmac_f32_e32 v7, v86, v25
	v_fmac_f32_e32 v71, v93, v40
	v_fmac_f32_e32 v7, v87, v24
	v_fmac_f32_e32 v71, v94, v38
	v_mul_f32_e64 v24, |v7|, s27
	v_fmac_f32_e32 v71, v95, v36
	v_exp_f32_e32 v24, v24
	s_waitcnt lgkmcnt(1)
	v_fmac_f32_e32 v71, v96, v34
	v_fmac_f32_e32 v71, v97, v32
	v_fmac_f32_e32 v71, v98, v30
	v_fmac_f32_e32 v71, v99, v19
	v_add_f32_e32 v19, 1.0, v24
	v_cmp_gt_f32_e64 s[52:53], s26, v19
	s_waitcnt lgkmcnt(0)
	v_fmac_f32_e32 v71, v100, v20
	v_fmac_f32_e32 v71, v101, v21
	v_cndmask_b32_e64 v20, 0, 32, s[52:53]
	v_ldexp_f32 v19, v19, v20
	v_log_f32_e32 v19, v19
	v_fmac_f32_e32 v71, v102, v17
	v_fmac_f32_e32 v71, v103, v18
	v_mul_f32_e64 v18, |v71|, s27
	v_exp_f32_e32 v18, v18
	v_mul_f32_e32 v17, 0x3f317217, v19
	v_fma_f32 v17, v19, s79, -v17
	v_fmac_f32_e32 v17, 0x3377d1cf, v19
	v_fmac_f32_e32 v17, 0x3f317217, v19
	v_cmp_lt_f32_e64 s[54:55], |v19|, s80
	v_add_f32_e32 v18, 1.0, v18
	v_min_f32_e32 v7, 0, v7
	v_cndmask_b32_e64 v17, v19, v17, s[54:55]
	v_cmp_gt_f32_e64 s[54:55], s26, v18
	v_and_b32_e32 v9, 0xffff0000, v9
	s_nop 0
	v_cndmask_b32_e64 v19, 0, 32, s[54:55]
	v_ldexp_f32 v18, v18, v19
	v_log_f32_e32 v18, v18
	v_cndmask_b32_e64 v19, 0, v225, s[52:53]
	v_sub_f32_e32 v17, v17, v19
	v_min_f32_e32 v19, 0, v71
	v_mul_f32_e32 v20, 0x3f317217, v18
	v_fma_f32 v20, v18, s79, -v20
	v_fmac_f32_e32 v20, 0x3377d1cf, v18
	v_fmac_f32_e32 v20, 0x3f317217, v18
	v_cmp_lt_f32_e64 s[52:53], |v18|, s80
	v_sub_f32_e32 v7, v7, v17
	v_mul_f32_e32 v17, 0x3d800000, v7
	v_cndmask_b32_e64 v18, v18, v20, s[52:53]
	v_cndmask_b32_e64 v20, 0, v225, s[54:55]
	v_sub_f32_e32 v18, v18, v20
	v_sub_f32_e32 v18, v19, v18
	v_mul_f32_e32 v19, 0x3d800000, v18
	v_mov_b32_e32 v14, v19
	v_mov_b32_e32 v13, v17
	s_nop 1
	v_add_f32_dpp v14, v14, v14 row_shr:1 row_mask:0xf bank_mask:0xf
	v_add_f32_dpp v13, v13, v13 row_shr:1 row_mask:0xf bank_mask:0xf
	s_nop 0
	v_add_f32_dpp v14, v14, v14 row_shr:2 row_mask:0xf bank_mask:0xf
	v_add_f32_dpp v13, v13, v13 row_shr:2 row_mask:0xf bank_mask:0xf
	s_nop 0
	v_add_f32_dpp v14, v14, v14 row_shr:4 row_mask:0xf bank_mask:0xf
	v_add_f32_dpp v13, v13, v13 row_shr:4 row_mask:0xf bank_mask:0xf
	s_nop 0
	v_add_f32_dpp v14, v14, v14 row_shr:8 row_mask:0xf bank_mask:0xf
	v_add_f32_dpp v13, v13, v13 row_shr:8 row_mask:0xf bank_mask:0xf
	s_nop 0
	v_add_f32_dpp v14, v14, v14 row_bcast:15 row_mask:0xa bank_mask:0xf
	v_add_f32_dpp v13, v13, v13 row_bcast:15 row_mask:0xa bank_mask:0xf
	s_nop 0
	v_add_f32_dpp v14, v14, v14 row_bcast:31 row_mask:0xc bank_mask:0xf
	v_add_f32_dpp v13, v13, v13 row_bcast:31 row_mask:0xc bank_mask:0xf
	s_nop 0
	v_readlane_b32 s98, v14, 63
	v_readlane_b32 s99, v13, 63
	s_nop 1
	v_mov_b32_e32 v15, s98
	v_mov_b32_e32 v16, s99
	s_waitcnt lgkmcnt(1)
	v_sub_f32_e32 v14, v15, v14
	s_waitcnt lgkmcnt(0)
	v_sub_f32_e32 v7, v16, v13
	v_fmac_f32_e32 v14, 0x3d800000, v18
	v_mul_f32_e32 v7, 0x3fb8aa3b, v7
	v_exp_f32_e32 v7, v7
	v_sub_f32_e32 v17, v15, v14
	v_mul_f32_e32 v17, 0x3fb8aa3b, v17
	v_exp_f32_e32 v17, v17
	v_mul_f32_e32 v7, v7, v9
	v_cvt_pk_bf16_f32 v7, v7, v1
	ds_write_b16 v6, v7 offset:33424
	v_mul_f32_e32 v7, v17, v9
	v_cvt_pk_bf16_f32 v7, v7, v1
	ds_write_b16 v6, v7 offset:42640
	s_and_saveexec_b64 s[4:5], s[40:41]
	s_xor_b64 s[14:15], exec, s[4:5]
	s_ashr_i32 s23, s22, 31
	s_or_saveexec_b64 s[14:15], s[14:15]
	v_mov_b64_e32 v[6:7], s[22:23]
	s_xor_b64 exec, exec, s[14:15]
	s_cbranch_execz .LBB0_132
	v_mul_f32_e32 v6, 0x3fb8aa3b, v16
	s_ashr_i32 s23, s22, 31
	v_exp_f32_e32 v6, v6
	s_lshl_b64 s[4:5], s[22:23], 2
	v_mul_f32_e32 v7, 0x3fb8aa3b, v15
	s_add_u32 s6, s18, s4
	v_exp_f32_e32 v7, v7
	s_addc_u32 s7, s21, s5
	s_add_u32 s4, s51, s4
	s_addc_u32 s5, s92, s5
	global_store_dword v1, v6, s[6:7] offset:28
	global_store_dword v1, v7, s[4:5] offset:28
	v_mov_b64_e32 v[6:7], s[22:23]
	s_branch .LBB0_132

; #define LAS __attribute__((address_space(3)))
; __global__ void __launch_bounds__(512, 2) mega(Args a) {
;     extern __shared__ __attribute__((aligned(16))) unsigned char lds_raw[];
;     cg::grid_group grid = cg::this_grid();
;     volatile LAS unsigned* bst = (volatile LAS unsigned*)((LAS unsigned char*)lds_raw + LDS_QWORD + 16);
;     if (threadIdx.x < 2) bst[threadIdx.x] = 0u;
;     __syncthreads();
;     const XcdBarrier bar = xcd_barrier_post((unsigned*)(a.ws + WS_CTL) + CW_BAR, bst);
;     if (a.coop == 0x7fffffff) grid.sync();
;     int dup = 0;
;     for (int ph = a.ph_lo; ph < a.ph_hi; ++ph) {
;         CArgs* ap = (CArgs*)__builtin_amdgcn_kernarg_segment_ptr(); asm volatile("" : "+s"(ap));
;         run_phase(*ap, ph, lds_raw, (LAS unsigned char*)lds_raw, dup);
;     ...
;         if (ph + 1 < a.ph_hi) { xcd_barrier(bar); for (int q = 0; q < PROBE_SYNC; ++q) xcd_barrier(bar); }
;     }
; }
	.amdhsa_kernel _Z4mega4Args
		.amdhsa_group_segment_fixed_size 0
		.amdhsa_private_segment_fixed_size 0
		.amdhsa_kernarg_size 512
		.amdhsa_user_sgpr_count 2
		.amdhsa_user_sgpr_dispatch_ptr 0
		.amdhsa_user_sgpr_queue_ptr 0
		.amdhsa_user_sgpr_kernarg_segment_ptr 1
		.amdhsa_user_sgpr_dispatch_id 0
		.amdhsa_user_sgpr_kernarg_preload_length 0
		.amdhsa_user_sgpr_kernarg_preload_offset 0
		.amdhsa_user_sgpr_private_segment_size 0
		.amdhsa_uses_dynamic_stack 0
		.amdhsa_enable_private_segment 0
		.amdhsa_system_sgpr_workgroup_id_x 1
		.amdhsa_system_sgpr_workgroup_id_y 0
		.amdhsa_system_sgpr_workgroup_id_z 0
		.amdhsa_system_sgpr_workgroup_info 0
		.amdhsa_system_vgpr_workitem_id 2
		.amdhsa_next_free_vgpr 256
		.amdhsa_next_free_sgpr 100
		.amdhsa_accum_offset 256
		.amdhsa_reserve_vcc 1
		.amdhsa_float_round_mode_32 0
		.amdhsa_float_round_mode_16_64 0
		.amdhsa_float_denorm_mode_32 3
		.amdhsa_float_denorm_mode_16_64 3
		.amdhsa_dx10_clamp 1
		.amdhsa_ieee_mode 1
		.amdhsa_fp16_overflow 0
		.amdhsa_tg_split 0
		.amdhsa_exception_fp_ieee_invalid_op 0
		.amdhsa_exception_fp_denorm_src 0
		.amdhsa_exception_fp_ieee_div_zero 0
		.amdhsa_exception_fp_ieee_overflow 0
		.amdhsa_exception_fp_ieee_underflow 0
		.amdhsa_exception_fp_ieee_inexact 0
		.amdhsa_exception_int_div_zero 0
	.end_amdhsa_kernel

; #define LAS __attribute__((address_space(3)))
; __global__ void __launch_bounds__(512, 2) mega(Args a) {
;     extern __shared__ __attribute__((aligned(16))) unsigned char lds_raw[];
;     cg::grid_group grid = cg::this_grid();
;     volatile LAS unsigned* bst = (volatile LAS unsigned*)((LAS unsigned char*)lds_raw + LDS_QWORD + 16);
;     if (threadIdx.x < 2) bst[threadIdx.x] = 0u;
;     __syncthreads();
;     const XcdBarrier bar = xcd_barrier_post((unsigned*)(a.ws + WS_CTL) + CW_BAR, bst);
;     if (a.coop == 0x7fffffff) grid.sync();
;     int dup = 0;
;     for (int ph = a.ph_lo; ph < a.ph_hi; ++ph) {
;         CArgs* ap = (CArgs*)__builtin_amdgcn_kernarg_segment_ptr(); asm volatile("" : "+s"(ap));
;         run_phase(*ap, ph, lds_raw, (LAS unsigned char*)lds_raw, dup);
;     ...
;         if (ph + 1 < a.ph_hi) { xcd_barrier(bar); for (int q = 0; q < PROBE_SYNC; ++q) xcd_barrier(bar); }
;     }
; }
amdhsa.kernels:
  - .agpr_count:     0
    .args:
      - .offset:         0
        .size:           256
        .value_kind:     by_value
      - .offset:         256
        .size:           4
        .value_kind:     hidden_block_count_x
      - .offset:         260
        .size:           4
        .value_kind:     hidden_block_count_y
      - .offset:         264
        .size:           4
        .value_kind:     hidden_block_count_z
      - .offset:         268
        .size:           2
        .value_kind:     hidden_group_size_x
      - .offset:         270
        .size:           2
        .value_kind:     hidden_group_size_y
      - .offset:         272
        .size:           2
        .value_kind:     hidden_group_size_z
      - .offset:         274
        .size:           2
        .value_kind:     hidden_remainder_x
      - .offset:         276
        .size:           2
        .value_kind:     hidden_remainder_y
      - .offset:         278
        .size:           2
        .value_kind:     hidden_remainder_z
      - .offset:         296
        .size:           8
        .value_kind:     hidden_global_offset_x
      - .offset:         304
        .size:           8
        .value_kind:     hidden_global_offset_y
      - .offset:         312
        .size:           8
        .value_kind:     hidden_global_offset_z
      - .offset:         320
        .size:           2
        .value_kind:     hidden_grid_dims
      - .offset:         344
        .size:           8
        .value_kind:     hidden_multigrid_sync_arg
      - .offset:         376
        .size:           4
        .value_kind:     hidden_dynamic_lds_size
    .group_segment_fixed_size: 0
    .kernarg_segment_align: 8
    .kernarg_segment_size: 512
    .language:       OpenCL C
    .language_version:
      - 2
      - 0
    .max_flat_workgroup_size: 512
    .name:           _Z4mega4Args
    .private_segment_fixed_size: 0
    .sgpr_count:     106
    .sgpr_spill_count: 119
    .symbol:         _Z4mega4Args.kd
    .uniform_work_group_size: 1
    .uses_dynamic_stack: false
    .vgpr_count:     256
    .vgpr_spill_count: 0
    .wavefront_size: 64
